# conv item tail (g/beta): dt_bias/a_log loaded once per phase, token's a value loaded at the start of the item (three dependent load round trips removed from every item)
# baseline (speedup 1.0000x reference)
; __device__ __forceinline__ void dn_conv_token4(const P& p, int m0, int lane) {
;     const bf16_t* PRE = (const bf16_t*)(p.ws + WS_DNPRE);
;     int s0, s1;
;     if (m0 < MLAT) { s0 = m0 & ~2047; s1 = s0 + 2048; } else { s0 = MLAT + ((m0 - MLAT) & ~255); s1 = s0 + 256; }
; #pragma unroll 1
;     for (int cgp = 0; cgp < 3; ++cgp) {
;         const int col = cgp * 512 + lane * 8;
;         f32x4 w[5][2];
;     ...
;         const int m = m0 + (lane >> 4), idx = lane & 15;
;         const float a = ((const float*)(p.ws + WS_AB))[(size_t)m * 16 + idx];
;         float r;
;         if (idx < 8) { const float xx = a + p.dt_bias[idx]; const float sp = fmaxf(xx, 0.f) + log1pf(__expf(-fabsf(xx))); r = -__expf(p.a_log[idx]) * sp; }
;         else r = 1.f / (1.f + __expf(-a));
.LBB0_453:
	s_andn2_b64 vcc, exec, s[6:7]
	s_cbranch_vccnz .LBB0_521
	v_readlane_b32 s6, v253, 61
	s_add_i32 s12, s6, s62
	s_lshl_b32 s13, s12, 2
	s_waitcnt lgkmcnt(0)
	s_add_u32 s16, s2, 0xfd00000
	s_addc_u32 s17, s3, 0
	s_add_u32 s18, s2, 0xff00000
	v_and_b32_e32 v109, 15, v144
	s_addc_u32 s19, s3, 0
	v_lshlrev_b32_e32 v0, 4, v110
	v_lshlrev_b32_e32 v2, 2, v109
	v_mov_b32_e32 v3, v1
	s_cmpk_lt_i32 s12, 0x400
	v_lshl_add_u64 v[74:75], s[2:3], 0, v[0:1]
	v_lshrrev_b32_e32 v108, 4, v110
	v_cmp_lt_u32_e64 s[6:7], 7, v109
	v_lshl_add_u64 v[76:77], s[8:9], 0, v[2:3]
	v_lshl_add_u64 v[78:79], s[74:75], 0, v[2:3]
	v_and_b32_e32 v124, 28, v2
	v_mov_b32_e32 v125, 0
	v_lshl_add_u64 v[126:127], s[8:9], 0, v[124:125]
	global_load_dword v122, v[126:127], off
	v_lshl_add_u64 v[126:127], s[74:75], 0, v[124:125]
	global_load_dword v123, v[126:127], off
	s_mov_b64 s[8:9], -1
	s_cmpk_lt_i32 s12, 0x400
	s_cbranch_scc1 .Lcv_lo
	s_add_i32 s98, s12, 0xfffffc00
	s_mul_i32 s98, s98, 3
	s_mov_b32 s99, 3
	s_branch .LBB0_488

; __device__ __forceinline__ void dn_conv_token4(const P& p, int m0, int lane) {
;     const bf16_t* PRE = (const bf16_t*)(p.ws + WS_DNPRE);
;     int s0, s1;
;     if (m0 < MLAT) { s0 = m0 & ~2047; s1 = s0 + 2048; } else { s0 = MLAT + ((m0 - MLAT) & ~255); s1 = s0 + 256; }
; #pragma unroll 1
;     for (int cgp = 0; cgp < 3; ++cgp) {
;         const int col = cgp * 512 + lane * 8;
;         f32x4 w[5][2];
; #pragma unroll
;         for (int j = 0; j < 5; ++j) { w[j][0] = *(const f32x4*)(p.conv_w + j * 1536 + col); w[j][1] = *(const f32x4*)(p.conv_w + j * 1536 + col + 4); }
;         u32x4 xr[8];
; #pragma unroll
;         for (int r = 0; r < 8; ++r) { const int mm = m0 + r - 2; xr[r] = (mm >= s0 && mm < s1) ? *(const u32x4*)(PRE + (size_t)mm * 1536 + col) : (u32x4){0u, 0u, 0u, 0u}; }
;     ...
;         const int m = m0 + (lane >> 4), idx = lane & 15;
;         const float a = ((const float*)(p.ws + WS_AB))[(size_t)m * 16 + idx];
.LBB0_491:
	s_mul_i32 s9, s91, 0xc00
	s_mul_hi_i32 s8, s91, 0xc00
	s_add_u32 s12, s89, s9
	s_addc_u32 s13, s90, s8
	s_mul_i32 s9, s92, 0xc00
	s_mul_hi_i32 s8, s92, 0xc00
	s_add_u32 s14, s89, s9
	s_addc_u32 s15, s90, s8
	s_mul_i32 s9, s93, 0xc00
	s_mul_hi_i32 s8, s93, 0xc00
	s_add_u32 s20, s89, s9
	s_addc_u32 s21, s90, s8
	s_mul_i32 s9, s94, 0xc00
	s_mul_hi_i32 s8, s94, 0xc00
	s_add_u32 s22, s89, s9
	s_addc_u32 s23, s90, s8
	s_add_i32 s8, s95, s88
	s_lshl_b32 s24, s8, 2
	v_or_b32_e32 v124, s24, v108
	v_ashrrev_i32_e32 v125, 31, v124
	v_lshlrev_b64 v[124:125], 4, v[124:125]
	v_or_b32_e32 v124, v124, v109
	v_lshl_add_u64 v[126:127], v[124:125], 2, s[16:17]
	global_load_dword v128, v[126:127], off
	s_and_b32 s9, s24, 0xfffff800
	s_and_b32 s11, s24, 0x7fffff00
	s_add_i32 s10, s9, 0x800
	s_add_i32 s25, s11, 0x100
	s_cmpk_lt_i32 s8, 0x1000
	s_cselect_b32 s48, s10, s25
	s_cselect_b32 s49, s9, s11
	s_add_i32 s10, s24, -2
	s_cmp_ge_i32 s10, s49
	s_cselect_b64 s[8:9], -1, 0
	s_cmp_lt_i32 s10, s48
	s_cselect_b64 s[10:11], -1, 0
	s_and_b64 s[26:27], s[8:9], s[10:11]
	s_add_i32 s10, s24, -1
	s_cmp_ge_i32 s10, s49
	s_cselect_b64 s[8:9], -1, 0
	s_cmp_lt_i32 s10, s48
	s_cselect_b64 s[10:11], -1, 0
	s_and_b64 s[28:29], s[8:9], s[10:11]
	s_cmp_ge_i32 s24, s49
	s_cselect_b64 s[8:9], -1, 0
	s_cmp_lt_i32 s24, s48
	s_cselect_b64 s[10:11], -1, 0
	s_and_b64 s[30:31], s[8:9], s[10:11]
	s_ashr_i32 s25, s24, 31
	s_or_b32 s8, s24, 1
	s_cmp_ge_i32 s8, s49
	s_cselect_b64 s[10:11], -1, 0
	s_cmp_lt_i32 s8, s48
	s_cselect_b64 s[34:35], -1, 0
	s_and_b64 s[34:35], s[10:11], s[34:35]
	s_ashr_i32 s9, s8, 31
	s_or_b32 s10, s24, 2
	s_cmp_ge_i32 s10, s49
	s_cselect_b64 s[40:41], -1, 0
	s_cmp_lt_i32 s10, s48
	s_cselect_b64 s[42:43], -1, 0
	s_and_b64 s[40:41], s[40:41], s[42:43]
	s_ashr_i32 s11, s10, 31
	s_or_b32 s72, s24, 3
	s_cmp_ge_i32 s72, s49
	s_cselect_b64 s[42:43], -1, 0
	s_cmp_lt_i32 s72, s48
	s_cselect_b64 s[44:45], -1, 0
	s_and_b64 s[42:43], s[42:43], s[44:45]
	s_ashr_i32 s73, s72, 31
	s_add_i32 s46, s24, 4
	s_cmp_ge_i32 s46, s49
	s_cselect_b64 s[44:45], -1, 0
	s_cmp_lt_i32 s46, s48
	s_cselect_b64 s[46:47], -1, 0
	s_and_b64 s[44:45], s[44:45], s[46:47]
	s_add_i32 s50, s24, 5
	s_cmp_ge_i32 s50, s49
	s_cselect_b64 s[46:47], -1, 0
	s_cmp_lt_i32 s50, s48
	s_cselect_b64 s[48:49], -1, 0
	s_and_b64 s[46:47], s[46:47], s[48:49]
	s_lshl_b64 s[48:49], s[24:25], 10
	s_lshl_b64 s[76:77], s[8:9], 10
	s_lshl_b64 s[80:81], s[10:11], 10
	s_lshl_b64 s[82:83], s[72:73], 10
	s_mov_b64 s[84:85], 0
	s_mov_b64 s[86:87], s[2:3]
	s_branch .LBB0_493

; __device__ __forceinline__ void dn_conv_token4(const P& p, int m0, int lane) {
;     ...
;     {
;         const int m = m0 + (lane >> 4), idx = lane & 15;
;         const float a = ((const float*)(p.ws + WS_AB))[(size_t)m * 16 + idx];
;         float r;
;         if (idx < 8) { const float xx = a + p.dt_bias[idx]; const float sp = fmaxf(xx, 0.f) + log1pf(__expf(-fabsf(xx))); r = -__expf(p.a_log[idx]) * sp; }
;         else r = 1.f / (1.f + __expf(-a));
;         ((float*)(p.ws + WS_GB))[(size_t)m * 16 + idx] = r;
;     }
.LBB0_517:
	v_or_b32_e32 v2, s24, v108
	v_ashrrev_i32_e32 v3, 31, v2
	v_lshlrev_b64 v[2:3], 4, v[2:3]
	v_or_b32_e32 v2, v2, v109
	s_waitcnt vmcnt(1)
	v_mov_b32_e32 v5, v128
	s_and_saveexec_b64 s[8:9], s[6:7]
	s_xor_b64 s[8:9], exec, s[8:9]
	s_cbranch_execz .LBB0_519
	v_mul_f32_e32 v4, 0xbfb8aa3b, v5
	v_exp_f32_e32 v4, v4
	s_nop 0
	v_add_f32_e32 v4, 1.0, v4
	v_div_scale_f32 v5, s[10:11], v4, v4, 1.0
	v_rcp_f32_e32 v6, v5
	v_div_scale_f32 v7, vcc, 1.0, v4, 1.0
	v_fma_f32 v8, -v5, v6, 1.0
	v_fmac_f32_e32 v6, v8, v6
	v_mul_f32_e32 v8, v7, v6
	v_fma_f32 v9, -v5, v8, v7
	v_fmac_f32_e32 v8, v9, v6
	v_fma_f32 v5, -v5, v8, v7
	v_div_fmas_f32 v5, v5, v6, v8
	v_div_fixup_f32 v4, v5, v4, 1.0
.LBB0_519:
	s_andn2_saveexec_b64 s[8:9], s[8:9]
	s_cbranch_execz .LBB0_490
	v_mov_b32_e32 v4, v122
	s_mov_b32 s1, 0xbfb8aa3b
	v_add_f32_e32 v4, v5, v4
	v_max_f32_e32 v18, 0, v4
	v_mul_f32_e64 v4, |v4|, s1
	v_exp_f32_e32 v19, v4
	s_mov_b32 s1, 0x3f2aaaab
	v_add_f32_e32 v6, 1.0, v19
	v_add_f32_e32 v4, -1.0, v6
	v_sub_f32_e32 v5, v4, v6
	v_add_f32_e32 v5, 1.0, v5
	v_sub_f32_e32 v4, v19, v4
	v_add_f32_e32 v7, v4, v5
	v_frexp_mant_f32_e32 v4, v6
	v_cmp_gt_f32_e32 vcc, s1, v4
	v_cvt_f64_f32_e32 v[4:5], v6
	v_frexp_exp_i32_f64_e32 v4, v[4:5]
	v_subbrev_co_u32_e32 v12, vcc, 0, v4, vcc
	v_sub_u32_e32 v4, 0, v12
	v_ldexp_f32 v5, v6, v4
	v_add_f32_e32 v6, -1.0, v5
	v_add_f32_e32 v8, 1.0, v5
	v_ldexp_f32 v4, v7, v4
	v_add_f32_e32 v7, 1.0, v6
	v_add_f32_e32 v9, -1.0, v8
	v_sub_f32_e32 v7, v5, v7
	v_sub_f32_e32 v5, v5, v9
	v_add_f32_e32 v7, v4, v7
	v_add_f32_e32 v4, v4, v5
	v_add_f32_e32 v13, v8, v4
	v_rcp_f32_e32 v15, v13
	v_sub_f32_e32 v5, v13, v8
	v_sub_f32_e32 v14, v4, v5
	v_add_f32_e32 v5, v6, v7
	v_mul_f32_e32 v17, v5, v15
	v_sub_f32_e32 v4, v5, v6
	v_mul_f32_e32 v6, v13, v17
	v_fma_f32 v8, v17, v13, -v6
	v_fmac_f32_e32 v8, v17, v14
	v_sub_f32_e32 v16, v7, v4
	v_add_f32_e32 v4, v6, v8
	v_sub_f32_e32 v7, v5, v4
	v_pk_add_f32 v[10:11], v[4:5], v[6:7] neg_lo:[0,1] neg_hi:[0,1]
	v_mov_b32_e32 v9, v4
	v_pk_add_f32 v[4:5], v[10:11], v[8:9] neg_lo:[0,1] neg_hi:[0,1]
	s_mov_b32 s1, 0x3f317218
	v_add_f32_e32 v5, v16, v5
	v_add_f32_e32 v4, v4, v5
	v_add_f32_e32 v5, v7, v4
	v_mul_f32_e32 v16, v15, v5
	v_mul_f32_e32 v6, v13, v16
	v_fma_f32 v8, v16, v13, -v6
	v_fmac_f32_e32 v8, v16, v14
	v_sub_f32_e32 v7, v7, v5
	v_add_f32_e32 v13, v4, v7
	v_add_f32_e32 v4, v6, v8
	v_sub_f32_e32 v7, v5, v4
	v_pk_add_f32 v[10:11], v[4:5], v[6:7] neg_lo:[0,1] neg_hi:[0,1]
	v_mov_b32_e32 v9, v4
	v_pk_add_f32 v[4:5], v[10:11], v[8:9] neg_lo:[0,1] neg_hi:[0,1]
	s_nop 0
	v_add_f32_e32 v5, v13, v5
	v_add_f32_e32 v4, v4, v5
	v_add_f32_e32 v5, v17, v16
	v_add_f32_e32 v4, v7, v4
	v_sub_f32_e32 v6, v5, v17
	v_mul_f32_e32 v4, v15, v4
	v_sub_f32_e32 v6, v16, v6
	v_add_f32_e32 v6, v6, v4
	v_add_f32_e32 v8, v5, v6
	v_mul_f32_e32 v9, v8, v8
	v_mov_b32_e32 v4, 0x3ecc95a3
	v_fmamk_f32 v4, v9, 0x3e9b6dac, v4
	v_fmaak_f32 v143, v9, v4, 0x3f2aaada
	v_cvt_f32_i32_e32 v4, v12
	v_sub_f32_e32 v5, v8, v5
	v_sub_f32_e32 v5, v6, v5
	v_ldexp_f32 v10, v5, 1
	v_mul_f32_e32 v5, v8, v9
	v_ldexp_f32 v7, v8, 1
	v_pk_mul_f32 v[8:9], v[4:5], v[142:143]
	s_nop 0
	v_fma_f32 v6, v4, s1, -v8
	v_fmac_f32_e32 v6, 0xb102e308, v4
	v_pk_add_f32 v[4:5], v[8:9], v[6:7]
	s_mov_b32 s1, 0x7f800000
	v_sub_f32_e32 v7, v5, v7
	v_sub_f32_e32 v7, v9, v7
	v_add_f32_e32 v11, v10, v7
	v_mov_b32_e32 v10, v8
	v_pk_add_f32 v[8:9], v[4:5], v[8:9] neg_lo:[0,1] neg_hi:[0,1]
	v_pk_add_f32 v[12:13], v[4:5], v[10:11]
	v_mov_b32_e32 v7, v4
	v_mov_b32_e32 v9, v13
	v_pk_add_f32 v[14:15], v[6:7], v[8:9] neg_lo:[0,1] neg_hi:[0,1]
	v_pk_add_f32 v[6:7], v[6:7], v[8:9]
	v_mov_b32_e32 v10, v11
	v_pk_add_f32 v[8:9], v[6:7], v[4:5] op_sel:[1,0] op_sel_hi:[0,1] neg_lo:[0,1] neg_hi:[0,1]
	v_pk_add_f32 v[16:17], v[12:13], v[8:9] op_sel_hi:[1,0] neg_lo:[0,1] neg_hi:[0,1]
	v_mov_b32_e32 v12, v13
	v_mov_b32_e32 v13, v7
	v_pk_mov_b32 v[8:9], v[4:5], v[8:9] op_sel:[1,0]
	v_mov_b32_e32 v11, v4
	v_pk_add_f32 v[8:9], v[12:13], v[8:9] neg_lo:[0,1] neg_hi:[0,1]
	v_mov_b32_e32 v16, v14
	v_pk_add_f32 v[4:5], v[10:11], v[8:9] neg_lo:[0,1] neg_hi:[0,1]
	v_mov_b32_e32 v15, v7
	v_pk_add_f32 v[8:9], v[16:17], v[4:5]
	v_cmp_neq_f32_e32 vcc, s1, v19
	v_pk_add_f32 v[10:11], v[8:9], v[8:9] op_sel:[0,1] op_sel_hi:[1,0]
	s_mov_b32 s1, 0x33800000
	v_pk_add_f32 v[6:7], v[6:7], v[10:11] op_sel:[1,0] op_sel_hi:[0,1]
	v_mov_b32_e32 v9, v6
	v_pk_add_f32 v[12:13], v[8:9], v[14:15] neg_lo:[0,1] neg_hi:[0,1]
	v_mov_b32_e32 v5, v10
	v_sub_f32_e32 v7, v8, v12
	v_pk_add_f32 v[4:5], v[4:5], v[12:13] neg_lo:[0,1] neg_hi:[0,1]
	v_sub_f32_e32 v7, v14, v7
	v_add_f32_e32 v4, v4, v7
	v_add_f32_e32 v4, v4, v5
	v_add_f32_e32 v4, v6, v4
	v_mov_b32_e32 v5, 0x7f800000
	v_cndmask_b32_e32 v4, v5, v4, vcc
	v_cmp_ngt_f32_e32 vcc, -1.0, v19
	v_mov_b32_e32 v5, 0xff800000
	s_nop 0
	v_cndmask_b32_e32 v4, v201, v4, vcc
	v_cmp_neq_f32_e32 vcc, -1.0, v19
	s_nop 1
	v_cndmask_b32_e32 v4, v5, v4, vcc
	v_mov_b32_e32 v5, v123
	v_cmp_lt_f32_e64 vcc, |v19|, s1
	v_mul_f32_e32 v5, 0x3fb8aa3b, v5
	v_exp_f32_e32 v5, v5
	v_cndmask_b32_e32 v4, v4, v19, vcc
	v_add_f32_e32 v4, v18, v4
	v_mul_f32_e64 v4, v4, -v5
	s_branch .LBB0_490
